# m1,m2,m6,m8 + m9a: W_a epilogue gate loads all in flight (was 16 serialized load->wait->store rounds)
# baseline (speedup 1.0000x reference)
;     __device__ __forceinline__ void operator()(const pg8::f32x4 (&acc)[2][2][4][2], const pg8::Unit& u, int wr, int wc, int fr, int fq) const {
;     ...
;         for (int ai = 0; ai < 2; ++ai)
; #pragma unroll
;             for (int m = 0; m < 4; ++m) {
;                 const int row = u.pm * 256 + ai * 128 + wr * 64 + m * 16 + fr;
; #pragma unroll
;                 for (int bj = 0; bj < 2; ++bj) {
;                     const int col = u.pn * 256 + bj * 128 + wc * 32 + 8 * fq;
;                     f(w, row, col, acc[ai][bj][m][0], acc[ai][bj][m][1]);
;                 }
.LBB0_327:
	v_mov_b32_e32 v138, v222
	s_lshl_b32 s2, s20, 8
	v_readfirstlane_b32 s1, v138
	s_ashr_i32 s13, s1, 2
	s_lshr_b32 s1, s1, 1
	s_andn2_b32 s13, s13, 63
	v_and_or_b32 v139, v138, 15, s2
	s_lshl_b32 s0, s0, 8
	s_and_b32 s1, s1, 0x60
	s_mov_b64 s[22:23], s[30:31]
	v_add_u32_e32 v140, s13, v139
	s_or_b32 s0, s1, s0
	v_lshrrev_b32_e32 v138, 1, v138
	v_and_or_b32 v138, v138, 24, s0
	s_add_u32 s20, s22, 0x14a00000
	v_ashrrev_i32_e32 v141, 31, v140
	s_addc_u32 s21, s23, 0
	v_lshlrev_b64 v[144:145], 11, v[140:141]
	v_ashrrev_i32_e32 v139, 31, v138
	s_add_u32 s22, s22, 0x8a00000
	v_lshl_add_u64 v[146:147], s[20:21], 0, v[144:145]
	v_lshlrev_b64 v[138:139], 1, v[138:139]
	s_addc_u32 s23, s23, 0
	v_lshl_add_u64 v[150:151], v[146:147], 0, v[138:139]
	v_lshl_add_u64 v[148:149], s[22:23], 0, v[144:145]
	global_load_dwordx4 v[156:159], v[150:151], off
	global_load_dwordx4 v[160:163], v[150:151], off offset:256
	s_mov_b64 s[98:99], 0x8000
	v_lshl_add_u64 v[244:245], v[150:151], 0, s[98:99]
	global_load_dwordx4 v[164:167], v[244:245], off
	global_load_dwordx4 v[168:171], v[244:245], off offset:256
	s_mov_b64 s[98:99], 0x10000
	v_lshl_add_u64 v[244:245], v[150:151], 0, s[98:99]
	global_load_dwordx4 v[172:175], v[244:245], off
	global_load_dwordx4 v[176:179], v[244:245], off offset:256
	s_mov_b64 s[98:99], 0x18000
	v_lshl_add_u64 v[244:245], v[150:151], 0, s[98:99]
	global_load_dwordx4 v[180:183], v[244:245], off
	global_load_dwordx4 v[184:187], v[244:245], off offset:256
	s_mov_b64 s[98:99], 0x40000
	v_lshl_add_u64 v[244:245], v[150:151], 0, s[98:99]
	global_load_dwordx4 v[188:191], v[244:245], off
	global_load_dwordx4 v[194:197], v[244:245], off offset:256
	s_mov_b64 s[98:99], 0x48000
	v_lshl_add_u64 v[244:245], v[150:151], 0, s[98:99]
	global_load_dwordx4 v[202:205], v[244:245], off
	global_load_dwordx4 v[212:215], v[244:245], off offset:256
	s_mov_b64 s[98:99], 0x50000
	v_lshl_add_u64 v[244:245], v[150:151], 0, s[98:99]
	global_load_dwordx4 v[216:219], v[244:245], off
	global_load_dwordx4 v[232:235], v[244:245], off offset:256
	s_mov_b64 s[98:99], 0x58000
	v_lshl_add_u64 v[244:245], v[150:151], 0, s[98:99]
	global_load_dwordx4 v[236:239], v[244:245], off
	global_load_dwordx4 v[240:243], v[244:245], off offset:256
	v_lshl_add_u64 v[148:149], v[148:149], 0, v[138:139]
	s_andn2_b64 vcc, exec, s[6:7]
	s_waitcnt vmcnt(15)
	v_lshlrev_b32_e32 v152, 16, v156
	v_and_b32_e32 v153, 0xffff0000, v156
	v_lshlrev_b32_e32 v144, 16, v157
	v_and_b32_e32 v145, 0xffff0000, v157
	v_lshlrev_b32_e32 v154, 16, v158
	v_and_b32_e32 v155, 0xffff0000, v158
	v_lshlrev_b32_e32 v146, 16, v159
	v_and_b32_e32 v147, 0xffff0000, v159
	v_pk_mul_f32 v[126:127], v[126:127], v[144:145]
	v_pk_mul_f32 v[124:125], v[124:125], v[152:153]
	v_pk_mul_f32 v[144:145], v[122:123], v[146:147]
	v_pk_mul_f32 v[122:123], v[120:121], v[154:155]
	v_cvt_pk_bf16_f32 v120, v124, v125
	v_cvt_pk_bf16_f32 v121, v126, v127
	v_cvt_pk_bf16_f32 v122, v122, v123
	v_cvt_pk_bf16_f32 v123, v144, v145
	global_store_dwordx4 v[148:149], v[120:123], off
	s_waitcnt vmcnt(15)
	v_lshlrev_b32_e32 v124, 16, v160
	v_and_b32_e32 v125, 0xffff0000, v160
	v_lshlrev_b32_e32 v120, 16, v161
	v_and_b32_e32 v121, 0xffff0000, v161
	v_lshlrev_b32_e32 v126, 16, v162
	v_and_b32_e32 v127, 0xffff0000, v162
	v_lshlrev_b32_e32 v122, 16, v163
	v_and_b32_e32 v123, 0xffff0000, v163
	v_pk_mul_f32 v[118:119], v[118:119], v[120:121]
	v_pk_mul_f32 v[116:117], v[116:117], v[124:125]
	v_pk_mul_f32 v[120:121], v[114:115], v[122:123]
	v_pk_mul_f32 v[114:115], v[112:113], v[126:127]
	v_cvt_pk_bf16_f32 v112, v116, v117
	v_cvt_pk_bf16_f32 v113, v118, v119
	v_cvt_pk_bf16_f32 v114, v114, v115
	v_cvt_pk_bf16_f32 v115, v120, v121
	global_store_dwordx4 v[148:149], v[112:115], off offset:256
	s_nop 1
	s_nop 1
	v_or_b32_e32 v112, 16, v140
	v_ashrrev_i32_e32 v113, 31, v112
	v_lshlrev_b64 v[112:113], 11, v[112:113]
	v_lshl_add_u64 v[114:115], s[20:21], 0, v[112:113]
	v_lshl_add_u64 v[118:119], v[114:115], 0, v[138:139]
	v_lshl_add_u64 v[116:117], s[22:23], 0, v[112:113]
	v_lshl_add_u64 v[116:117], v[116:117], 0, v[138:139]
	s_waitcnt vmcnt(15)
	v_lshlrev_b32_e32 v120, 16, v164
	v_and_b32_e32 v121, 0xffff0000, v164
	v_lshlrev_b32_e32 v112, 16, v165
	v_and_b32_e32 v113, 0xffff0000, v165
	v_lshlrev_b32_e32 v122, 16, v166
	v_and_b32_e32 v123, 0xffff0000, v166
	v_lshlrev_b32_e32 v114, 16, v167
	v_and_b32_e32 v115, 0xffff0000, v167
	v_pk_mul_f32 v[110:111], v[110:111], v[112:113]
	v_pk_mul_f32 v[108:109], v[108:109], v[120:121]
	v_pk_mul_f32 v[112:113], v[106:107], v[114:115]
	v_pk_mul_f32 v[106:107], v[104:105], v[122:123]
	v_cvt_pk_bf16_f32 v104, v108, v109
	v_cvt_pk_bf16_f32 v105, v110, v111
	v_cvt_pk_bf16_f32 v106, v106, v107
	v_cvt_pk_bf16_f32 v107, v112, v113
	global_store_dwordx4 v[116:117], v[104:107], off
	s_waitcnt vmcnt(15)
	v_lshlrev_b32_e32 v108, 16, v168
	v_and_b32_e32 v109, 0xffff0000, v168
	v_lshlrev_b32_e32 v104, 16, v169
	v_and_b32_e32 v105, 0xffff0000, v169
	v_lshlrev_b32_e32 v110, 16, v170
	v_and_b32_e32 v111, 0xffff0000, v170
	v_lshlrev_b32_e32 v106, 16, v171
	v_and_b32_e32 v107, 0xffff0000, v171
	v_pk_mul_f32 v[102:103], v[102:103], v[104:105]
	v_pk_mul_f32 v[100:101], v[100:101], v[108:109]
	v_pk_mul_f32 v[104:105], v[98:99], v[106:107]
	v_pk_mul_f32 v[98:99], v[96:97], v[110:111]
	v_cvt_pk_bf16_f32 v96, v100, v101
	v_cvt_pk_bf16_f32 v97, v102, v103
	v_cvt_pk_bf16_f32 v98, v98, v99
	v_cvt_pk_bf16_f32 v99, v104, v105
	global_store_dwordx4 v[116:117], v[96:99], off offset:256
	s_nop 1
	s_nop 1
	v_or_b32_e32 v96, 32, v140
	v_ashrrev_i32_e32 v97, 31, v96
	v_lshlrev_b64 v[96:97], 11, v[96:97]
	v_lshl_add_u64 v[98:99], s[20:21], 0, v[96:97]
	v_lshl_add_u64 v[102:103], v[98:99], 0, v[138:139]
	v_lshl_add_u64 v[100:101], s[22:23], 0, v[96:97]
	v_lshl_add_u64 v[100:101], v[100:101], 0, v[138:139]
	s_waitcnt vmcnt(15)
;     __device__ __forceinline__ void operator()(const pg8::f32x4 (&acc)[2][2][4][2], const pg8::Unit& u, int wr, int wc, int fr, int fq) const {
;     ...
;         for (int ai = 0; ai < 2; ++ai)
; #pragma unroll
;             for (int m = 0; m < 4; ++m) {
;                 const int row = u.pm * 256 + ai * 128 + wr * 64 + m * 16 + fr;
; #pragma unroll
;                 for (int bj = 0; bj < 2; ++bj) {
;                     const int col = u.pn * 256 + bj * 128 + wc * 32 + 8 * fq;
;                     f(w, row, col, acc[ai][bj][m][0], acc[ai][bj][m][1]);
;                 }
	v_lshlrev_b32_e32 v104, 16, v172
	v_and_b32_e32 v105, 0xffff0000, v172
	v_lshlrev_b32_e32 v96, 16, v173
	v_and_b32_e32 v97, 0xffff0000, v173
	v_lshlrev_b32_e32 v106, 16, v174
	v_and_b32_e32 v107, 0xffff0000, v174
	v_lshlrev_b32_e32 v98, 16, v175
	v_and_b32_e32 v99, 0xffff0000, v175
	v_pk_mul_f32 v[94:95], v[94:95], v[96:97]
	v_pk_mul_f32 v[92:93], v[92:93], v[104:105]
	v_pk_mul_f32 v[96:97], v[90:91], v[98:99]
	v_pk_mul_f32 v[90:91], v[88:89], v[106:107]
	v_cvt_pk_bf16_f32 v88, v92, v93
	v_cvt_pk_bf16_f32 v89, v94, v95
	v_cvt_pk_bf16_f32 v90, v90, v91
	v_cvt_pk_bf16_f32 v91, v96, v97
	global_store_dwordx4 v[100:101], v[88:91], off
	s_waitcnt vmcnt(15)
	v_lshlrev_b32_e32 v92, 16, v176
	v_and_b32_e32 v93, 0xffff0000, v176
	v_lshlrev_b32_e32 v88, 16, v177
	v_and_b32_e32 v89, 0xffff0000, v177
	v_lshlrev_b32_e32 v94, 16, v178
	v_and_b32_e32 v95, 0xffff0000, v178
	v_lshlrev_b32_e32 v90, 16, v179
	v_and_b32_e32 v91, 0xffff0000, v179
	v_pk_mul_f32 v[86:87], v[86:87], v[88:89]
	v_pk_mul_f32 v[84:85], v[84:85], v[92:93]
	v_pk_mul_f32 v[88:89], v[82:83], v[90:91]
	v_pk_mul_f32 v[82:83], v[80:81], v[94:95]
	v_cvt_pk_bf16_f32 v80, v84, v85
	v_cvt_pk_bf16_f32 v81, v86, v87
	v_cvt_pk_bf16_f32 v82, v82, v83
	v_cvt_pk_bf16_f32 v83, v88, v89
	global_store_dwordx4 v[100:101], v[80:83], off offset:256
	s_nop 1
	s_nop 1
	v_or_b32_e32 v80, 48, v140
	v_ashrrev_i32_e32 v81, 31, v80
	v_lshlrev_b64 v[80:81], 11, v[80:81]
	v_lshl_add_u64 v[82:83], s[20:21], 0, v[80:81]
	v_lshl_add_u64 v[86:87], s[22:23], 0, v[80:81]
	v_lshl_add_u64 v[80:81], v[82:83], 0, v[138:139]
	s_waitcnt vmcnt(15)
	v_lshlrev_b32_e32 v88, 16, v180
	v_and_b32_e32 v89, 0xffff0000, v180
	v_lshlrev_b32_e32 v90, 16, v181
	v_and_b32_e32 v91, 0xffff0000, v181
	v_lshlrev_b32_e32 v92, 16, v182
	v_and_b32_e32 v93, 0xffff0000, v182
	v_lshlrev_b32_e32 v84, 16, v183
	v_and_b32_e32 v85, 0xffff0000, v183
	v_pk_mul_f32 v[78:79], v[78:79], v[90:91]
	v_pk_mul_f32 v[76:77], v[76:77], v[88:89]
	v_pk_mul_f32 v[84:85], v[74:75], v[84:85]
	v_pk_mul_f32 v[74:75], v[72:73], v[92:93]
	v_lshl_add_u64 v[82:83], v[86:87], 0, v[138:139]
	v_cvt_pk_bf16_f32 v72, v76, v77
	v_cvt_pk_bf16_f32 v73, v78, v79
	v_cvt_pk_bf16_f32 v74, v74, v75
	v_cvt_pk_bf16_f32 v75, v84, v85
	global_store_dwordx4 v[82:83], v[72:75], off
	s_waitcnt vmcnt(15)
	v_lshlrev_b32_e32 v76, 16, v184
	v_and_b32_e32 v77, 0xffff0000, v184
	v_lshlrev_b32_e32 v72, 16, v185
	v_and_b32_e32 v73, 0xffff0000, v185
	v_lshlrev_b32_e32 v78, 16, v186
	v_and_b32_e32 v79, 0xffff0000, v186
	v_lshlrev_b32_e32 v74, 16, v187
	v_and_b32_e32 v75, 0xffff0000, v187
	v_pk_mul_f32 v[70:71], v[70:71], v[72:73]
	v_pk_mul_f32 v[68:69], v[68:69], v[76:77]
	v_pk_mul_f32 v[72:73], v[66:67], v[74:75]
	v_pk_mul_f32 v[66:67], v[64:65], v[78:79]
	v_cvt_pk_bf16_f32 v64, v68, v69
	v_cvt_pk_bf16_f32 v65, v70, v71
	v_cvt_pk_bf16_f32 v66, v66, v67
	v_cvt_pk_bf16_f32 v67, v72, v73
	global_store_dwordx4 v[82:83], v[64:67], off offset:256
	s_nop 1
	s_nop 1
	v_add_u32_e32 v64, 0x80, v140
	v_ashrrev_i32_e32 v65, 31, v64
	v_lshlrev_b64 v[64:65], 11, v[64:65]
	v_lshl_add_u64 v[66:67], s[20:21], 0, v[64:65]
	v_lshl_add_u64 v[70:71], v[66:67], 0, v[138:139]
	v_lshl_add_u64 v[68:69], s[22:23], 0, v[64:65]
	s_waitcnt vmcnt(15)
	v_lshlrev_b32_e32 v72, 16, v188
	v_and_b32_e32 v73, 0xffff0000, v188
	v_lshlrev_b32_e32 v74, 16, v189
	v_and_b32_e32 v75, 0xffff0000, v189
	v_lshlrev_b32_e32 v76, 16, v190
	v_and_b32_e32 v77, 0xffff0000, v190
	v_lshlrev_b32_e32 v66, 16, v191
	v_and_b32_e32 v67, 0xffff0000, v191
	v_pk_mul_f32 v[62:63], v[62:63], v[74:75]
	v_pk_mul_f32 v[60:61], v[60:61], v[72:73]
	v_pk_mul_f32 v[66:67], v[58:59], v[66:67]
	v_pk_mul_f32 v[58:59], v[56:57], v[76:77]
	v_lshl_add_u64 v[64:65], v[68:69], 0, v[138:139]
	v_cvt_pk_bf16_f32 v56, v60, v61
	v_cvt_pk_bf16_f32 v57, v62, v63
	v_cvt_pk_bf16_f32 v58, v58, v59
	v_cvt_pk_bf16_f32 v59, v66, v67
	global_store_dwordx4 v[64:65], v[56:59], off
	s_waitcnt vmcnt(15)
	v_lshlrev_b32_e32 v60, 16, v194
	v_and_b32_e32 v61, 0xffff0000, v194
	v_lshlrev_b32_e32 v56, 16, v195
	v_and_b32_e32 v57, 0xffff0000, v195
	v_lshlrev_b32_e32 v62, 16, v196
	v_and_b32_e32 v63, 0xffff0000, v196
	v_lshlrev_b32_e32 v58, 16, v197
	v_and_b32_e32 v59, 0xffff0000, v197
	v_pk_mul_f32 v[54:55], v[54:55], v[56:57]
	v_pk_mul_f32 v[52:53], v[52:53], v[60:61]
	v_pk_mul_f32 v[56:57], v[50:51], v[58:59]
	v_pk_mul_f32 v[50:51], v[48:49], v[62:63]
	v_cvt_pk_bf16_f32 v48, v52, v53
	v_cvt_pk_bf16_f32 v49, v54, v55
	v_cvt_pk_bf16_f32 v50, v50, v51
	v_cvt_pk_bf16_f32 v51, v56, v57
	global_store_dwordx4 v[64:65], v[48:51], off offset:256
	s_nop 1
	s_nop 1
	v_add_u32_e32 v48, 0x90, v140
	v_ashrrev_i32_e32 v49, 31, v48
	v_lshlrev_b64 v[48:49], 11, v[48:49]
	v_lshl_add_u64 v[50:51], s[20:21], 0, v[48:49]
	v_lshl_add_u64 v[54:55], v[50:51], 0, v[138:139]
	v_lshl_add_u64 v[52:53], s[22:23], 0, v[48:49]
	v_lshl_add_u64 v[52:53], v[52:53], 0, v[138:139]
	s_waitcnt vmcnt(15)
;     __device__ __forceinline__ void operator()(const pg8::f32x4 (&acc)[2][2][4][2], const pg8::Unit& u, int wr, int wc, int fr, int fq) const {
;     ...
;         for (int ai = 0; ai < 2; ++ai)
; #pragma unroll
;             for (int m = 0; m < 4; ++m) {
;                 const int row = u.pm * 256 + ai * 128 + wr * 64 + m * 16 + fr;
; #pragma unroll
;                 for (int bj = 0; bj < 2; ++bj) {
;                     const int col = u.pn * 256 + bj * 128 + wc * 32 + 8 * fq;
;                     f(w, row, col, acc[ai][bj][m][0], acc[ai][bj][m][1]);
;                 }
	v_lshlrev_b32_e32 v56, 16, v202
	v_and_b32_e32 v57, 0xffff0000, v202
	v_lshlrev_b32_e32 v48, 16, v203
	v_and_b32_e32 v49, 0xffff0000, v203
	v_lshlrev_b32_e32 v58, 16, v204
	v_and_b32_e32 v59, 0xffff0000, v204
	v_lshlrev_b32_e32 v50, 16, v205
	v_and_b32_e32 v51, 0xffff0000, v205
	v_pk_mul_f32 v[46:47], v[46:47], v[48:49]
	v_pk_mul_f32 v[44:45], v[44:45], v[56:57]
	v_pk_mul_f32 v[48:49], v[42:43], v[50:51]
	v_pk_mul_f32 v[42:43], v[40:41], v[58:59]
	v_cvt_pk_bf16_f32 v40, v44, v45
	v_cvt_pk_bf16_f32 v41, v46, v47
	v_cvt_pk_bf16_f32 v42, v42, v43
	v_cvt_pk_bf16_f32 v43, v48, v49
	global_store_dwordx4 v[52:53], v[40:43], off
	s_waitcnt vmcnt(15)
	v_lshlrev_b32_e32 v44, 16, v212
	v_and_b32_e32 v45, 0xffff0000, v212
	v_lshlrev_b32_e32 v40, 16, v213
	v_and_b32_e32 v41, 0xffff0000, v213
	v_lshlrev_b32_e32 v46, 16, v214
	v_and_b32_e32 v47, 0xffff0000, v214
	v_lshlrev_b32_e32 v42, 16, v215
	v_and_b32_e32 v43, 0xffff0000, v215
	v_pk_mul_f32 v[38:39], v[38:39], v[40:41]
	v_pk_mul_f32 v[36:37], v[36:37], v[44:45]
	v_pk_mul_f32 v[40:41], v[34:35], v[42:43]
	v_pk_mul_f32 v[34:35], v[32:33], v[46:47]
	v_cvt_pk_bf16_f32 v32, v36, v37
	v_cvt_pk_bf16_f32 v33, v38, v39
	v_cvt_pk_bf16_f32 v34, v34, v35
	v_cvt_pk_bf16_f32 v35, v40, v41
	global_store_dwordx4 v[52:53], v[32:35], off offset:256
	s_nop 1
	s_nop 1
	v_add_u32_e32 v32, 0xa0, v140
	v_ashrrev_i32_e32 v33, 31, v32
	v_lshlrev_b64 v[32:33], 11, v[32:33]
	v_lshl_add_u64 v[34:35], s[20:21], 0, v[32:33]
	v_lshl_add_u64 v[38:39], v[34:35], 0, v[138:139]
	v_lshl_add_u64 v[36:37], s[22:23], 0, v[32:33]
	v_lshl_add_u64 v[36:37], v[36:37], 0, v[138:139]
	s_waitcnt vmcnt(15)
	v_lshlrev_b32_e32 v40, 16, v216
	v_and_b32_e32 v41, 0xffff0000, v216
	v_lshlrev_b32_e32 v32, 16, v217
	v_and_b32_e32 v33, 0xffff0000, v217
	v_lshlrev_b32_e32 v42, 16, v218
	v_and_b32_e32 v43, 0xffff0000, v218
	v_lshlrev_b32_e32 v34, 16, v219
	v_and_b32_e32 v35, 0xffff0000, v219
	v_pk_mul_f32 v[30:31], v[30:31], v[32:33]
	v_pk_mul_f32 v[28:29], v[28:29], v[40:41]
	v_pk_mul_f32 v[32:33], v[26:27], v[34:35]
	v_pk_mul_f32 v[26:27], v[24:25], v[42:43]
	v_cvt_pk_bf16_f32 v24, v28, v29
	v_cvt_pk_bf16_f32 v25, v30, v31
	v_cvt_pk_bf16_f32 v26, v26, v27
	v_cvt_pk_bf16_f32 v27, v32, v33
	global_store_dwordx4 v[36:37], v[24:27], off
	s_waitcnt vmcnt(15)
	v_lshlrev_b32_e32 v28, 16, v232
	v_and_b32_e32 v29, 0xffff0000, v232
	v_lshlrev_b32_e32 v24, 16, v233
	v_and_b32_e32 v25, 0xffff0000, v233
	v_lshlrev_b32_e32 v30, 16, v234
	v_and_b32_e32 v31, 0xffff0000, v234
	v_lshlrev_b32_e32 v26, 16, v235
	v_and_b32_e32 v27, 0xffff0000, v235
	v_pk_mul_f32 v[22:23], v[22:23], v[24:25]
	v_pk_mul_f32 v[20:21], v[20:21], v[28:29]
	v_pk_mul_f32 v[24:25], v[18:19], v[26:27]
	v_pk_mul_f32 v[18:19], v[16:17], v[30:31]
	v_cvt_pk_bf16_f32 v16, v20, v21
	v_cvt_pk_bf16_f32 v17, v22, v23
	v_cvt_pk_bf16_f32 v18, v18, v19
	v_cvt_pk_bf16_f32 v19, v24, v25
	global_store_dwordx4 v[36:37], v[16:19], off offset:256
	s_nop 1
	s_nop 1
	v_add_u32_e32 v16, 0xb0, v140
	v_ashrrev_i32_e32 v17, 31, v16
	v_lshlrev_b64 v[16:17], 11, v[16:17]
	v_lshl_add_u64 v[18:19], s[20:21], 0, v[16:17]
	v_lshl_add_u64 v[22:23], v[18:19], 0, v[138:139]
	v_lshl_add_u64 v[20:21], s[22:23], 0, v[16:17]
	v_lshl_add_u64 v[20:21], v[20:21], 0, v[138:139]
	s_mov_b64 s[20:21], -1
	s_waitcnt vmcnt(15)
	v_lshlrev_b32_e32 v24, 16, v236
	v_and_b32_e32 v25, 0xffff0000, v236
	v_lshlrev_b32_e32 v16, 16, v237
	v_and_b32_e32 v17, 0xffff0000, v237
	v_lshlrev_b32_e32 v26, 16, v238
	v_and_b32_e32 v27, 0xffff0000, v238
	v_lshlrev_b32_e32 v18, 16, v239
	v_and_b32_e32 v19, 0xffff0000, v239
	v_pk_mul_f32 v[14:15], v[14:15], v[16:17]
	v_pk_mul_f32 v[12:13], v[12:13], v[24:25]
	v_pk_mul_f32 v[16:17], v[10:11], v[18:19]
	v_pk_mul_f32 v[10:11], v[8:9], v[26:27]
	v_cvt_pk_bf16_f32 v8, v12, v13
	v_cvt_pk_bf16_f32 v9, v14, v15
	v_cvt_pk_bf16_f32 v10, v10, v11
	v_cvt_pk_bf16_f32 v11, v16, v17
	global_store_dwordx4 v[20:21], v[8:11], off
	s_waitcnt vmcnt(15)
	v_lshlrev_b32_e32 v12, 16, v240
	v_and_b32_e32 v13, 0xffff0000, v240
	v_lshlrev_b32_e32 v8, 16, v241
	v_and_b32_e32 v9, 0xffff0000, v241
	v_lshlrev_b32_e32 v14, 16, v242
	v_and_b32_e32 v15, 0xffff0000, v242
	v_lshlrev_b32_e32 v10, 16, v243
	v_and_b32_e32 v11, 0xffff0000, v243
	v_pk_mul_f32 v[6:7], v[6:7], v[8:9]
	v_pk_mul_f32 v[4:5], v[4:5], v[12:13]
	v_pk_mul_f32 v[8:9], v[2:3], v[10:11]
	v_pk_mul_f32 v[2:3], v[0:1], v[14:15]
	v_cvt_pk_bf16_f32 v0, v4, v5
	v_cvt_pk_bf16_f32 v1, v6, v7
	v_cvt_pk_bf16_f32 v2, v2, v3
	v_cvt_pk_bf16_f32 v3, v8, v9
	global_store_dwordx4 v[20:21], v[0:3], off offset:256
	s_cbranch_vccnz .LBB0_316
	s_andn2_b64 vcc, exec, s[8:9]
	s_cbranch_vccnz .LBB0_315
	s_barrier
	s_branch .LBB0_315
